# MLA tile loop: one static s_setprio 1 for waves 4-7 (reset after the loop)
# baseline (speedup 1.0000x reference)
.LBB0_472:
	s_waitcnt vmcnt(0) lgkmcnt(0)
	v_lshlrev_b32_e32 v50, 16, v20
	v_and_b32_e32 v51, 0xffff0000, v20
	v_lshlrev_b32_e32 v52, 16, v16
	v_and_b32_e32 v53, 0xffff0000, v16
	s_lshl_b32 s26, s50, 3
	v_pk_mul_f32 v[54:55], v[28:29], v[52:53]
	v_pk_mul_f32 v[28:29], v[28:29], v[50:51]
	s_ashr_i32 s27, s26, 31
	v_pk_fma_f32 v[54:55], v[24:25], v[50:51], v[54:55] neg_lo:[0,0,1] neg_hi:[0,0,1]
	v_pk_fma_f32 v[24:25], v[24:25], v[52:53], v[28:29]
	v_lshlrev_b32_e32 v16, 16, v17
	v_and_b32_e32 v17, 0xffff0000, v17
	s_add_u32 s28, s6, s26
	v_cvt_pk_bf16_f32 v220, v24, v25
	v_lshlrev_b32_e32 v20, 16, v21
	v_and_b32_e32 v21, 0xffff0000, v21
	v_pk_mul_f32 v[24:25], v[30:31], v[16:17]
	s_addc_u32 s29, s7, s27
	v_pk_fma_f32 v[24:25], v[26:27], v[20:21], v[24:25] neg_lo:[0,0,1] neg_hi:[0,0,1]
	v_pk_mul_f32 v[20:21], v[30:31], v[20:21]
	s_lshl_b64 s[28:29], s[28:29], 10
	v_pk_fma_f32 v[16:17], v[26:27], v[16:17], v[20:21]
	v_lshlrev_b32_e32 v20, 16, v18
	v_and_b32_e32 v21, 0xffff0000, v18
	s_add_u32 s54, s38, s28
	v_cvt_pk_bf16_f32 v217, v24, v25
	v_cvt_pk_bf16_f32 v221, v16, v17
	v_lshlrev_b32_e32 v16, 16, v22
	v_and_b32_e32 v17, 0xffff0000, v22
	v_pk_mul_f32 v[24:25], v[44:45], v[20:21]
	s_addc_u32 s55, s39, s29
	s_lshl_b64 s[28:29], s[20:21], 1
	v_pk_fma_f32 v[24:25], v[36:37], v[16:17], v[24:25] neg_lo:[0,0,1] neg_hi:[0,0,1]
	v_pk_mul_f32 v[16:17], v[44:45], v[16:17]
	s_add_u32 s54, s54, s28
	v_and_b32_e32 v234, 63, v48
	v_pk_fma_f32 v[16:17], v[36:37], v[20:21], v[16:17]
	s_addc_u32 s55, s55, s29
	v_cvt_pk_bf16_f32 v222, v16, v17
	v_lshrrev_b32_e32 v16, 3, v234
	s_add_u32 s54, s54, 0x80
	v_lshlrev_b32_e32 v17, 10, v16
	v_bitop3_b32 v16, v16, v48, 7 bitop3:0x78
	s_addc_u32 s55, s55, 0
	s_lshl_b32 s50, s50, 10
	s_add_i32 s56, 0, 0xc000
	v_lshl_or_b32 v236, v16, 4, v17
	s_add_i32 s57, s50, s56
	s_mov_b32 s58, m0
	s_mov_b32 m0, s57
	s_nop 0
	global_load_lds_dwordx4 v236, s[54:55]
	s_mov_b32 m0, s58
	s_lshl_b32 s54, s51, 3
	s_ashr_i32 s55, s54, 31
	s_add_u32 s54, s6, s54
	s_addc_u32 s55, s7, s55
	s_lshl_b64 s[54:55], s[54:55], 10
	s_add_u32 s54, s38, s54
	s_addc_u32 s55, s39, s55
	s_add_u32 s54, s54, s28
	s_addc_u32 s55, s55, s29
	s_add_u32 s54, s54, 0x80
	v_lshlrev_b32_e32 v16, 4, v48
	s_addc_u32 s55, s55, 0
	s_lshl_b32 s51, s51, 10
	v_and_b32_e32 v16, 0x3f0, v16
	s_add_i32 s56, s51, s56
	s_mov_b32 s57, m0
	s_mov_b32 m0, s56
	s_nop 0
	global_load_lds_dwordx4 v236, s[54:55]
	s_mov_b32 m0, s57
	v_add_u32_e32 v70, 0, v16
	v_lshlrev_b32_e32 v44, 16, v19
	v_and_b32_e32 v45, 0xffff0000, v19
	s_waitcnt vmcnt(0)
	s_barrier
	ds_read_b128 v[50:53], v70
	v_lshlrev_b32_e32 v36, 16, v23
	v_and_b32_e32 v37, 0xffff0000, v23
	v_pk_mul_f32 v[16:17], v[46:47], v[44:45]
	v_cvt_pk_bf16_f32 v216, v54, v55
	v_pk_fma_f32 v[16:17], v[38:39], v[36:37], v[16:17] neg_lo:[0,0,1] neg_hi:[0,0,1]
	v_pk_mul_f32 v[36:37], v[46:47], v[36:37]
	ds_read_b128 v[54:57], v70 offset:1024
	v_pk_fma_f32 v[36:37], v[38:39], v[44:45], v[36:37]
	v_lshlrev_b32_e32 v38, 16, v8
	v_and_b32_e32 v39, 0xffff0000, v8
	v_cvt_pk_bf16_f32 v223, v36, v37
	v_lshlrev_b32_e32 v36, 16, v12
	v_and_b32_e32 v37, 0xffff0000, v12
	v_pk_mul_f32 v[44:45], v[40:41], v[38:39]
	v_lshlrev_b32_e32 v8, 16, v9
	v_pk_fma_f32 v[44:45], v[32:33], v[36:37], v[44:45] neg_lo:[0,0,1] neg_hi:[0,0,1]
	v_pk_mul_f32 v[36:37], v[40:41], v[36:37]
	v_and_b32_e32 v9, 0xffff0000, v9
	v_pk_fma_f32 v[32:33], v[32:33], v[38:39], v[36:37]
	v_lshlrev_b32_e32 v12, 16, v13
	v_cvt_pk_bf16_f32 v228, v32, v33
	v_and_b32_e32 v13, 0xffff0000, v13
	v_pk_mul_f32 v[32:33], v[42:43], v[8:9]
	v_cvt_pk_bf16_f32 v218, v24, v25
	v_pk_fma_f32 v[32:33], v[34:35], v[12:13], v[32:33] neg_lo:[0,0,1] neg_hi:[0,0,1]
	v_pk_mul_f32 v[12:13], v[42:43], v[12:13]
	v_cvt_pk_bf16_f32 v219, v16, v17
	v_pk_fma_f32 v[8:9], v[34:35], v[8:9], v[12:13]
	v_lshlrev_b32_e32 v12, 16, v10
	v_and_b32_e32 v13, 0xffff0000, v10
	s_waitcnt lgkmcnt(1)
	v_mfma_f32_32x32x16_bf16 v[16:31], v[50:53], v[184:187], 0
	v_cvt_pk_bf16_f32 v225, v32, v33
	v_cvt_pk_bf16_f32 v229, v8, v9
	v_lshlrev_b32_e32 v8, 16, v14
	v_and_b32_e32 v9, 0xffff0000, v14
	v_mul_f32_e64 v32, v4, v12
	v_mul_f32_e64 v33, v5, v13
	v_cvt_pk_bf16_f32 v224, v44, v45
	v_pk_fma_f32 v[32:33], v[0:1], v[8:9], v[32:33] neg_lo:[0,0,1] neg_hi:[0,0,1]
	ds_read_b128 v[58:61], v70 offset:2048
	ds_read_b128 v[62:65], v70 offset:3072
	v_cvt_pk_bf16_f32 v226, v32, v33
	v_mfma_f32_32x32x16_bf16 v[32:47], v[50:53], v[200:203], 0
	v_mul_f32_e64 v4, v4, v8
	v_mul_f32_e64 v5, v5, v9
	v_readlane_b32 s68, v254, 32
	v_fma_f32 v0, v0, v12, v4
	v_fma_f32 v1, v1, v13, v5
	v_lshlrev_b32_e32 v4, 16, v11
	v_and_b32_e32 v5, 0xffff0000, v11
	v_cvt_pk_bf16_f32 v230, v0, v1
	v_lshlrev_b32_e32 v0, 16, v15
	s_waitcnt lgkmcnt(2)
	v_mfma_f32_32x32x16_bf16 v[16:31], v[54:57], v[188:191], v[16:31]
	v_and_b32_e32 v1, 0xffff0000, v15
	v_mul_f32_e64 v8, v6, v4
	v_mul_f32_e64 v9, v7, v5
	v_readlane_b32 s69, v254, 33
	v_fma_f32 v8, v2, v0, -v8
	v_fma_f32 v9, v3, v1, -v9
	v_pk_mul_f32 v[0:1], v[6:7], v[0:1]
	v_readlane_b32 s70, v254, 34
	v_pk_fma_f32 v[0:1], v[2:3], v[4:5], v[0:1]
	v_mfma_f32_32x32x16_bf16 v[32:47], v[54:57], v[204:207], v[32:47]
	v_readlane_b32 s71, v254, 35
	v_readlane_b32 s72, v254, 36
	v_readlane_b32 s73, v254, 37
	v_readlane_b32 s74, v254, 38
	v_readlane_b32 s75, v254, 39
	v_readlane_b32 s76, v254, 40
	v_readlane_b32 s77, v254, 41
	v_readlane_b32 s78, v254, 42
	v_readlane_b32 s79, v254, 43
	v_readlane_b32 s80, v254, 44
	v_readlane_b32 s81, v254, 45
	v_readlane_b32 s82, v254, 46
	v_readlane_b32 s83, v254, 47
	s_mov_b32 s68, s69
	v_cvt_pk_bf16_f32 v227, v8, v9
	v_cvt_pk_bf16_f32 v231, v0, v1
	s_mov_b32 s70, s69
	s_mov_b32 s71, s69
	s_mov_b32 s72, s69
	s_mov_b32 s73, s69
	s_mov_b32 s74, s69
	s_mov_b32 s75, s69
	s_mov_b32 s76, s69
	s_mov_b32 s77, s69
	s_mov_b32 s78, s69
	s_mov_b32 s79, s69
	s_mov_b32 s80, s69
	s_mov_b32 s81, s69
	s_mov_b32 s82, s69
	s_mov_b32 s83, s69
	v_mov_b64_e32 v[0:1], s[68:69]
	v_mov_b64_e32 v[2:3], s[70:71]
	v_mov_b64_e32 v[4:5], s[72:73]
	v_mov_b64_e32 v[6:7], s[74:75]
	v_mov_b64_e32 v[8:9], s[76:77]
	v_mov_b64_e32 v[10:11], s[78:79]
	v_mov_b64_e32 v[12:13], s[80:81]
	v_mov_b64_e32 v[14:15], s[82:83]
	s_lshl_b32 s68, s52, 4
	s_lshl_b32 s52, s53, 4
	s_ashr_i32 s56, s68, 31
	s_ashr_i32 s57, s52, 31
	s_lshl_b64 s[54:55], s[12:13], 23
	s_lshl_b64 s[26:27], s[26:27], 10
	s_add_u32 s26, s54, s26
	s_waitcnt lgkmcnt(1)
	v_mfma_f32_32x32x16_bf16 v[16:31], v[58:61], v[192:195], v[16:31]
	s_addc_u32 s27, s55, s27
	s_add_u32 s26, s26, s28
	s_addc_u32 s27, s27, s29
	s_add_u32 s54, s54, 0x1d220000
	s_addc_u32 s55, s55, 0
	s_lshl_b64 s[28:29], s[18:19], 10
	s_add_u32 s28, s54, s28
	v_mfma_f32_32x32x16_bf16 v[32:47], v[58:61], v[208:211], v[32:47]
	s_addc_u32 s29, s55, s29
	ds_read_b128 v[66:69], v70 offset:4096
	s_add_u32 s22, s22, s20
	s_addc_u32 s23, s23, s21
	s_lshl_b64 s[22:23], s[22:23], 1
	s_add_u32 s22, s28, s22
	s_addc_u32 s23, s29, s23
	s_waitcnt lgkmcnt(1)
	v_mfma_f32_32x32x16_bf16 v[16:31], v[62:65], v[196:199], v[16:31]
	s_lshl_b64 s[12:13], s[12:13], 19
	s_add_u32 s28, s12, 0x1f201f80
	s_addc_u32 s29, s13, 0
	s_lshl_b64 s[12:13], s[18:19], 6
	s_add_u32 s18, s28, s12
	ds_read_b128 v[70:73], v70 offset:5120
	s_addc_u32 s19, s29, s13
	v_mfma_f32_32x32x16_bf16 v[32:47], v[62:65], v[212:215], v[32:47]
	s_lshl_b64 s[12:13], s[24:25], 1
	s_add_u32 s18, s18, s12
	s_addc_u32 s19, s19, s13
	s_lshl_b64 s[12:13], s[16:17], 10
	s_add_u32 s24, s54, s12
	s_addc_u32 s25, s55, s13
	s_add_u32 s12, s20, s52
	s_waitcnt lgkmcnt(1)
	v_mfma_f32_32x32x16_bf16 v[16:31], v[66:69], v[216:219], v[16:31]
	s_addc_u32 s13, s21, s57
	s_lshl_b64 s[12:13], s[12:13], 1
	s_add_u32 s24, s24, s12
	s_addc_u32 s25, s25, s13
	s_lshl_b64 s[12:13], s[16:17], 6
	s_mov_b32 s53, s69
	s_add_u32 s16, s28, s12
	v_mfma_f32_32x32x16_bf16 v[32:47], v[66:69], v[224:227], v[32:47]
	s_addc_u32 s17, s29, s13
	s_lshl_b64 s[12:13], s[52:53], 1
	s_add_u32 s16, s16, s12
	s_addc_u32 s17, s17, s13
	s_lshl_b64 s[12:13], s[14:15], 10
	s_add_u32 s52, s54, s12
	s_addc_u32 s53, s55, s13
	s_waitcnt lgkmcnt(0)
	v_mfma_f32_32x32x16_bf16 v[16:31], v[70:73], v[220:223], v[16:31]
	s_add_u32 s12, s20, s68
	s_addc_u32 s13, s21, s56
	s_lshl_b64 s[12:13], s[12:13], 1
	s_add_u32 s20, s52, s12
	s_addc_u32 s21, s53, s13
	s_lshl_b64 s[12:13], s[14:15], 6
	s_add_u32 s14, s28, s12
	v_mfma_f32_32x32x16_bf16 v[32:47], v[70:73], v[228:231], v[32:47]
	s_nop 3
	v_max_f32_e32 v17, v17, v17
	v_max_f32_e32 v16, v16, v16
	v_max_f32_e32 v16, v16, v17
	v_max3_f32 v16, v16, v18, v19
	s_addc_u32 s15, s29, s13
	s_mov_b32 s13, s69
	v_writelane_b32 v254, s12, 32
	s_nop 0
	v_max_f32_e32 v18, v33, v33
	v_max_f32_e32 v19, v32, v32
	v_max_f32_e32 v18, v19, v18
	v_max3_f32 v18, v18, v34, v35
	v_max3_f32 v18, v18, v36, v37
	v_max3_f32 v18, v18, v38, v39
	v_max3_f32 v16, v16, v20, v21
	v_max3_f32 v18, v18, v40, v41
	v_writelane_b32 v254, s13, 33
	v_max3_f32 v16, v16, v22, v23
	v_max3_f32 v18, v18, v42, v43
	v_writelane_b32 v254, s14, 34
	v_max3_f32 v16, v16, v24, v25
	v_max3_f32 v18, v18, v44, v45
	v_writelane_b32 v254, s15, 35
	v_max3_f32 v16, v16, v26, v27
	v_max3_f32 v18, v18, v46, v47
	v_writelane_b32 v254, s16, 36
	v_max3_f32 v16, v16, v28, v29
	v_mov_b32_e32 v19, v18
	v_writelane_b32 v254, s17, 37
	v_max3_f32 v16, v16, v30, v31
	v_permlane32_swap_b32_e32 v18, v19
	v_writelane_b32 v254, s18, 38
	v_mov_b32_e32 v17, v16
	v_max_f32_e32 v19, v19, v19
	v_max_f32_e32 v18, v18, v18
	v_writelane_b32 v254, s19, 39
	v_permlane32_swap_b32_e32 v16, v17
	v_max_f32_e32 v18, v18, v19
	v_writelane_b32 v254, s20, 40
	v_max3_f32 v16, v16, v17, v18
	v_writelane_b32 v254, s21, 41
	v_bfe_u32 v50, v48, 2, 2
	v_xor_b32_e32 v64, 0x80000000, v16
	v_lshlrev_b32_e32 v16, 9, v49
	v_lshlrev_b32_e32 v17, 4, v253
	v_lshlrev_b32_e32 v235, 2, v49
	v_writelane_b32 v254, s22, 42
	v_add3_u32 v237, 0, v16, v17
	v_or_b32_e32 v16, v235, v50
	v_lshlrev_b32_e32 v18, 3, v48
	v_writelane_b32 v254, s23, 43
	v_lshlrev_b32_e32 v17, 7, v16
	v_and_b32_e32 v18, 8, v18
	v_writelane_b32 v254, s24, 44
	v_add3_u32 v238, 0, v17, v18
	v_bfe_u32 v17, v48, 1, 1
	v_lshrrev_b32_e32 v18, 3, v48
	v_writelane_b32 v254, s25, 45
	v_and_or_b32 v17, v18, 2, v17
	v_writelane_b32 v254, s26, 46
	v_bitop3_b32 v18, v235, v17, v50 bitop3:0x36
	v_bitop3_b32 v16, v17, v16, 4 bitop3:0x36
	v_writelane_b32 v254, s27, 47
	s_lshl_b64 s[12:13], s[68:69], 1
	v_lshlrev_b32_e32 v239, 4, v18
	v_lshlrev_b32_e32 v240, 4, v16
	s_add_u32 s14, s14, s12
	v_mov_b32_e32 v232, v233
	v_mov_b64_e32 v[30:31], v[14:15]
	v_mov_b64_e32 v[46:47], v[14:15]
	v_mov_b64_e32 v[62:63], v[14:15]
	v_mov_b32_e32 v65, v64
	v_mov_b32_e32 v66, v64
	v_mov_b32_e32 v67, v64
	v_mov_b32_e32 v68, v64
	v_mov_b32_e32 v69, v64
	v_mov_b32_e32 v70, v64
	v_mov_b32_e32 v71, v64
	v_mov_b32_e32 v72, v64
	v_mov_b32_e32 v73, v64
	v_mov_b32_e32 v74, v64
	v_mov_b32_e32 v75, v64
	v_mov_b32_e32 v76, v64
	v_mov_b32_e32 v77, v64
	v_mov_b32_e32 v78, v64
	v_mov_b32_e32 v79, v64
	s_addc_u32 s15, s15, s13
	s_mov_b32 s29, 0
	v_mov_b64_e32 v[28:29], v[12:13]
	v_mov_b64_e32 v[26:27], v[10:11]
	v_mov_b64_e32 v[24:25], v[8:9]
	v_mov_b64_e32 v[22:23], v[6:7]
	v_mov_b64_e32 v[20:21], v[4:5]
	v_mov_b64_e32 v[18:19], v[2:3]
	v_mov_b64_e32 v[16:17], v[0:1]
	v_mov_b64_e32 v[44:45], v[12:13]
	v_mov_b64_e32 v[42:43], v[10:11]
	v_mov_b64_e32 v[40:41], v[8:9]
	v_mov_b64_e32 v[38:39], v[6:7]
	v_mov_b64_e32 v[36:37], v[4:5]
	v_mov_b64_e32 v[34:35], v[2:3]
	v_mov_b64_e32 v[32:33], v[0:1]
	v_mov_b64_e32 v[60:61], v[12:13]
	v_mov_b64_e32 v[58:59], v[10:11]
	v_mov_b64_e32 v[56:57], v[8:9]
	v_mov_b64_e32 v[54:55], v[6:7]
	v_mov_b64_e32 v[52:53], v[4:5]
	v_mov_b64_e32 v[50:51], v[2:3]
	v_mov_b64_e32 v[48:49], v[0:1]
	v_mov_b64_e32 v[244:245], v[232:233]
	s_mov_b64 s[82:83], 0x800
	s_movk_i32 s76, 0xfc00
	s_movk_i32 s78, 0x400
	s_movk_i32 s79, 0x180
	s_movk_i32 s80, 0x200
	v_readlane_b32 s77, v255, 0
	s_and_b32 s12, s29, 1
	s_mul_i32 s13, s12, 0x6000
	v_add_u32_e32 v242, s13, v237
	v_lshl_add_u32 v241, s12, 14, v238
	v_add_u32_e32 v232, v241, v240
	v_add_u32_e32 v241, v241, v239
	ds_read_b128 v[144:147], v242
	ds_read_b128 v[148:151], v242 offset:1024
	ds_read_b128 v[152:155], v242 offset:2048
	ds_read_b128 v[156:159], v242 offset:3072
	ds_read_b128 v[160:163], v242 offset:4096
	ds_read_b128 v[164:167], v242 offset:5120
	s_waitcnt lgkmcnt(5)
	v_mfma_f32_32x32x16_bf16 v[80:95], v[144:147], v[184:187], v[64:79]
	v_mfma_f32_32x32x16_bf16 v[96:111], v[144:147], v[200:203], v[64:79]
	ds_read_b128 v[144:147], v242 offset:6144
	s_waitcnt lgkmcnt(5)
	v_mfma_f32_32x32x16_bf16 v[80:95], v[148:151], v[188:191], v[80:95]
	v_mfma_f32_32x32x16_bf16 v[96:111], v[148:151], v[204:207], v[96:111]
	ds_read_b128 v[148:151], v242 offset:7168
	s_waitcnt lgkmcnt(5)
	v_mfma_f32_32x32x16_bf16 v[80:95], v[152:155], v[192:195], v[80:95]
	v_mfma_f32_32x32x16_bf16 v[96:111], v[152:155], v[208:211], v[96:111]
	ds_read_b128 v[152:155], v242 offset:8192
	s_waitcnt lgkmcnt(5)
	v_mfma_f32_32x32x16_bf16 v[80:95], v[156:159], v[196:199], v[80:95]
	v_mfma_f32_32x32x16_bf16 v[96:111], v[156:159], v[212:215], v[96:111]
	ds_read_b128 v[156:159], v242 offset:9216
	s_waitcnt lgkmcnt(5)
	v_mfma_f32_32x32x16_bf16 v[80:95], v[160:163], v[216:219], v[80:95]
	v_mfma_f32_32x32x16_bf16 v[96:111], v[160:163], v[224:227], v[96:111]
	ds_read_b128 v[160:163], v242 offset:10240
	s_waitcnt lgkmcnt(5)
	v_mfma_f32_32x32x16_bf16 v[80:95], v[164:167], v[220:223], v[80:95]
	v_mfma_f32_32x32x16_bf16 v[96:111], v[164:167], v[228:231], v[96:111]
	ds_read_b128 v[164:167], v242 offset:11264
	ds_read_b64_tr_b16 v[168:169], v241 offset:49152
	ds_read_b64_tr_b16 v[170:171], v241 offset:50176
	ds_read_b64_tr_b16 v[176:177], v232 offset:49152
	ds_read_b64_tr_b16 v[178:179], v232 offset:50176
	ds_read_b64_tr_b16 v[172:173], v241 offset:51200
	ds_read_b64_tr_b16 v[174:175], v241 offset:52224
	ds_read_b64_tr_b16 v[180:181], v232 offset:51200
	ds_read_b64_tr_b16 v[182:183], v232 offset:52224
	s_cmp_ge_u32 s46, 0x100
	s_cbranch_scc0 .Lprio_mla
	s_setprio 1
.Lprio_mla:
	s_add_i32 s28, s29, 1
	s_cmp_eq_u32 s29, 63
	s_cbranch_scc1 .LBB0_481

.LBB0_490:
	s_setprio 0
	v_mov_b32_e32 v152, v244
	v_mov_b32_e32 v153, v245
	s_lshl_b32 s2, s46, 2
	s_add_i32 s10, s2, 0
	s_add_i32 s10, s10, 0x1c800
	v_mov_b32_e32 v65, v152
	v_cmp_gt_u32_e64 s[2:3], 32, v234
	v_lshl_add_u32 v64, v253, 2, s10
	v_permlane32_swap_b32_e32 v152, v65
	s_and_saveexec_b64 s[8:9], s[2:3]
	s_cbranch_execz .LBB0_492
	v_add_f32_e32 v65, v152, v65
	v_div_scale_f32 v66, s[12:13], v65, v65, 1.0
	v_rcp_f32_e32 v67, v66
	v_div_scale_f32 v68, vcc, 1.0, v65, 1.0
	v_fma_f32 v69, -v66, v67, 1.0
	v_fmac_f32_e32 v67, v69, v67
	v_mul_f32_e32 v69, v68, v67
	v_fma_f32 v70, -v66, v69, v68
	v_fmac_f32_e32 v69, v70, v67
	v_fma_f32 v66, -v66, v69, v68
	v_div_fmas_f32 v66, v66, v67, v69
	v_div_fixup_f32 v65, v66, v65, 1.0
	ds_write_b32 v64, v65
